# EpiRes stores written through (sc1)
# speedup vs baseline: 1.0103x; 1.0018x over previous
.LBB0_772:
	s_and_b64 vcc, exec, s[4:5]
	s_cbranch_vccz .LBB0_774
	s_load_dwordx2 s[4:5], s[0:1], 0x148
	s_lshl_b32 s38, s70, 2
	v_lshlrev_b32_e32 v128, 2, v172
	v_mov_b32_e32 v129, v169
	s_waitcnt lgkmcnt(0)
	s_add_u32 s30, s4, s38
	s_addc_u32 s31, s5, 0
	v_lshl_add_u64 v[130:131], s[30:31], 0, v[128:129]
	s_lshl_b64 s[30:31], s[24:25], 2
	v_lshl_add_u64 v[130:131], v[130:131], 0, s[30:31]
	v_add_u32_e32 v250, s54, v192
	v_ashrrev_i32_e32 v251, 31, v250
	v_lshlrev_b64 v[250:251], 13, v[250:251]
	v_lshl_add_u64 v[164:165], v[130:131], 0, v[250:251]
	global_load_dwordx4 v[132:135], v[164:165], off
	global_load_dwordx4 v[136:139], v[164:165], off offset:64
	global_load_dwordx4 v[140:143], v[164:165], off offset:512
	global_load_dwordx4 v[144:147], v[164:165], off offset:576
	v_add_u32_e32 v250, s54, v194
	v_ashrrev_i32_e32 v251, 31, v250
	v_lshlrev_b64 v[250:251], 13, v[250:251]
	v_lshl_add_u64 v[166:167], v[130:131], 0, v[250:251]
	global_load_dwordx4 v[148:151], v[166:167], off
	global_load_dwordx4 v[152:155], v[166:167], off offset:64
	global_load_dwordx4 v[156:159], v[166:167], off offset:512
	global_load_dwordx4 v[160:163], v[166:167], off offset:576
	v_add_u32_e32 v250, s54, v195
	v_ashrrev_i32_e32 v251, 31, v250
	v_lshlrev_b64 v[250:251], 13, v[250:251]
	v_lshl_add_u64 v[224:225], v[130:131], 0, v[250:251]
	global_load_dwordx4 v[204:207], v[224:225], off
	global_load_dwordx4 v[208:211], v[224:225], off offset:64
	global_load_dwordx4 v[212:215], v[224:225], off offset:512
	global_load_dwordx4 v[216:219], v[224:225], off offset:576
	v_add_u32_e32 v250, s54, v196
	v_ashrrev_i32_e32 v251, 31, v250
	v_lshlrev_b64 v[250:251], 13, v[250:251]
	v_lshl_add_u64 v[248:249], v[130:131], 0, v[250:251]
	global_load_dwordx4 v[220:223], v[248:249], off
	global_load_dwordx4 v[232:235], v[248:249], off offset:64
	global_load_dwordx4 v[240:243], v[248:249], off offset:512
	global_load_dwordx4 v[244:247], v[248:249], off offset:576
	s_waitcnt vmcnt(8)
	v_pk_add_f32 v[132:133], v[124:125], v[132:133]
	v_pk_add_f32 v[134:135], v[126:127], v[134:135]
	global_store_dwordx4 v[164:165], v[132:135], off sc1
	v_pk_add_f32 v[136:137], v[120:121], v[136:137]
	v_pk_add_f32 v[138:139], v[122:123], v[138:139]
	global_store_dwordx4 v[164:165], v[136:139], off offset:64 sc1
	v_pk_add_f32 v[140:141], v[116:117], v[140:141]
	v_pk_add_f32 v[142:143], v[118:119], v[142:143]
	global_store_dwordx4 v[164:165], v[140:143], off offset:512 sc1
	v_pk_add_f32 v[144:145], v[112:113], v[144:145]
	v_pk_add_f32 v[146:147], v[114:115], v[146:147]
	global_store_dwordx4 v[164:165], v[144:147], off offset:576 sc1
	v_pk_add_f32 v[148:149], v[108:109], v[148:149]
	v_pk_add_f32 v[150:151], v[110:111], v[150:151]
	global_store_dwordx4 v[166:167], v[148:151], off sc1
	v_pk_add_f32 v[152:153], v[104:105], v[152:153]
	v_pk_add_f32 v[154:155], v[106:107], v[154:155]
	global_store_dwordx4 v[166:167], v[152:155], off offset:64 sc1
	v_pk_add_f32 v[156:157], v[100:101], v[156:157]
	v_pk_add_f32 v[158:159], v[102:103], v[158:159]
	global_store_dwordx4 v[166:167], v[156:159], off offset:512 sc1
	v_pk_add_f32 v[160:161], v[96:97], v[160:161]
	v_pk_add_f32 v[162:163], v[98:99], v[162:163]
	global_store_dwordx4 v[166:167], v[160:163], off offset:576 sc1
	s_nop 1
	v_add_u32_e32 v250, s54, v197
	v_ashrrev_i32_e32 v251, 31, v250
	v_lshlrev_b64 v[250:251], 13, v[250:251]
	v_lshl_add_u64 v[164:165], v[130:131], 0, v[250:251]
	global_load_dwordx4 v[132:135], v[164:165], off
	global_load_dwordx4 v[136:139], v[164:165], off offset:64
	global_load_dwordx4 v[140:143], v[164:165], off offset:512
	global_load_dwordx4 v[144:147], v[164:165], off offset:576
	v_add_u32_e32 v250, s54, v198
	v_ashrrev_i32_e32 v251, 31, v250
	v_lshlrev_b64 v[250:251], 13, v[250:251]
	v_lshl_add_u64 v[166:167], v[130:131], 0, v[250:251]
	global_load_dwordx4 v[148:151], v[166:167], off
	global_load_dwordx4 v[152:155], v[166:167], off offset:64
	global_load_dwordx4 v[156:159], v[166:167], off offset:512
	global_load_dwordx4 v[160:163], v[166:167], off offset:576
	s_waitcnt vmcnt(16)
	v_pk_add_f32 v[204:205], v[92:93], v[204:205]
	v_pk_add_f32 v[206:207], v[94:95], v[206:207]
	global_store_dwordx4 v[224:225], v[204:207], off sc1
	v_pk_add_f32 v[208:209], v[88:89], v[208:209]
	v_pk_add_f32 v[210:211], v[90:91], v[210:211]
	global_store_dwordx4 v[224:225], v[208:211], off offset:64 sc1
	v_pk_add_f32 v[212:213], v[84:85], v[212:213]
	v_pk_add_f32 v[214:215], v[86:87], v[214:215]
	global_store_dwordx4 v[224:225], v[212:215], off offset:512 sc1
	v_pk_add_f32 v[216:217], v[80:81], v[216:217]
	v_pk_add_f32 v[218:219], v[82:83], v[218:219]
	global_store_dwordx4 v[224:225], v[216:219], off offset:576 sc1
	v_pk_add_f32 v[220:221], v[76:77], v[220:221]
	v_pk_add_f32 v[222:223], v[78:79], v[222:223]
	global_store_dwordx4 v[248:249], v[220:223], off sc1
	v_pk_add_f32 v[232:233], v[72:73], v[232:233]
	v_pk_add_f32 v[234:235], v[74:75], v[234:235]
	global_store_dwordx4 v[248:249], v[232:235], off offset:64 sc1
	v_pk_add_f32 v[240:241], v[68:69], v[240:241]
	v_pk_add_f32 v[242:243], v[70:71], v[242:243]
	global_store_dwordx4 v[248:249], v[240:243], off offset:512 sc1
	v_pk_add_f32 v[244:245], v[64:65], v[244:245]
	v_pk_add_f32 v[246:247], v[66:67], v[246:247]
	global_store_dwordx4 v[248:249], v[244:247], off offset:576 sc1
	s_nop 1
	v_add_u32_e32 v250, s54, v199
	v_ashrrev_i32_e32 v251, 31, v250
	v_lshlrev_b64 v[250:251], 13, v[250:251]
	v_lshl_add_u64 v[224:225], v[130:131], 0, v[250:251]
	global_load_dwordx4 v[204:207], v[224:225], off
	global_load_dwordx4 v[208:211], v[224:225], off offset:64
	global_load_dwordx4 v[212:215], v[224:225], off offset:512
	global_load_dwordx4 v[216:219], v[224:225], off offset:576
	v_add_u32_e32 v250, s54, v200
	v_ashrrev_i32_e32 v251, 31, v250
	v_lshlrev_b64 v[250:251], 13, v[250:251]
	v_lshl_add_u64 v[248:249], v[130:131], 0, v[250:251]
	global_load_dwordx4 v[220:223], v[248:249], off
	global_load_dwordx4 v[232:235], v[248:249], off offset:64
	global_load_dwordx4 v[240:243], v[248:249], off offset:512
	global_load_dwordx4 v[244:247], v[248:249], off offset:576
	s_waitcnt vmcnt(16)
	v_pk_add_f32 v[132:133], v[60:61], v[132:133]
	v_pk_add_f32 v[134:135], v[62:63], v[134:135]
	global_store_dwordx4 v[164:165], v[132:135], off sc1
	v_pk_add_f32 v[136:137], v[56:57], v[136:137]
	v_pk_add_f32 v[138:139], v[58:59], v[138:139]
	global_store_dwordx4 v[164:165], v[136:139], off offset:64 sc1
	v_pk_add_f32 v[140:141], v[52:53], v[140:141]
	v_pk_add_f32 v[142:143], v[54:55], v[142:143]
	global_store_dwordx4 v[164:165], v[140:143], off offset:512 sc1
	v_pk_add_f32 v[144:145], v[48:49], v[144:145]
	v_pk_add_f32 v[146:147], v[50:51], v[146:147]
	global_store_dwordx4 v[164:165], v[144:147], off offset:576 sc1
	v_pk_add_f32 v[148:149], v[44:45], v[148:149]
	v_pk_add_f32 v[150:151], v[46:47], v[150:151]
	global_store_dwordx4 v[166:167], v[148:151], off sc1
	v_pk_add_f32 v[152:153], v[40:41], v[152:153]
	v_pk_add_f32 v[154:155], v[42:43], v[154:155]
	global_store_dwordx4 v[166:167], v[152:155], off offset:64 sc1
	v_pk_add_f32 v[156:157], v[36:37], v[156:157]
	v_pk_add_f32 v[158:159], v[38:39], v[158:159]
	global_store_dwordx4 v[166:167], v[156:159], off offset:512 sc1
	v_pk_add_f32 v[160:161], v[32:33], v[160:161]
	v_pk_add_f32 v[162:163], v[34:35], v[162:163]
	global_store_dwordx4 v[166:167], v[160:163], off offset:576 sc1
	s_waitcnt vmcnt(8)
	v_pk_add_f32 v[204:205], v[28:29], v[204:205]
	v_pk_add_f32 v[206:207], v[30:31], v[206:207]
	global_store_dwordx4 v[224:225], v[204:207], off sc1
	v_pk_add_f32 v[208:209], v[24:25], v[208:209]
	v_pk_add_f32 v[210:211], v[26:27], v[210:211]
	global_store_dwordx4 v[224:225], v[208:211], off offset:64 sc1
	v_pk_add_f32 v[212:213], v[20:21], v[212:213]
	v_pk_add_f32 v[214:215], v[22:23], v[214:215]
	global_store_dwordx4 v[224:225], v[212:215], off offset:512 sc1
	v_pk_add_f32 v[216:217], v[16:17], v[216:217]
	v_pk_add_f32 v[218:219], v[18:19], v[218:219]
	global_store_dwordx4 v[224:225], v[216:219], off offset:576 sc1
	v_pk_add_f32 v[220:221], v[12:13], v[220:221]
	v_pk_add_f32 v[222:223], v[14:15], v[222:223]
	global_store_dwordx4 v[248:249], v[220:223], off sc1
	v_pk_add_f32 v[232:233], v[8:9], v[232:233]
	v_pk_add_f32 v[234:235], v[10:11], v[234:235]
	global_store_dwordx4 v[248:249], v[232:235], off offset:64 sc1
	v_pk_add_f32 v[240:241], v[4:5], v[240:241]
	v_pk_add_f32 v[242:243], v[6:7], v[242:243]
	global_store_dwordx4 v[248:249], v[240:243], off offset:512 sc1
	v_pk_add_f32 v[244:245], v[0:1], v[244:245]
	v_pk_add_f32 v[246:247], v[2:3], v[246:247]
	global_store_dwordx4 v[248:249], v[244:247], off offset:576 sc1
